# v30 + zpost wave_sum butterflies: xor-1/2/4/8 steps via v_mov_b32_dpp instead of ds_swizzle (bit-identical), waits tightened to lgkmcnt(0)
# baseline (speedup 1.0000x reference)
; __device__ __forceinline__ float bf2f(bf16_t v) { return __uint_as_float((unsigned)v << 16); }
; __device__ __forceinline__ unsigned f2bf(float f) { unsigned u = __float_as_uint(f); return (u + 0x7fffu + ((u >> 16) & 1u)) >> 16; }
; #define SWZ_XOR(v, X) __int_as_float(__builtin_amdgcn_ds_swizzle(__float_as_int(v), ((X) << 10) | 0x1f))
; __device__ __forceinline__ float wave_sum(float v) {
;     v += SWZ_XOR(v, 1); v += SWZ_XOR(v, 2); v += SWZ_XOR(v, 4); v += SWZ_XOR(v, 8); v += SWZ_XOR(v, 16);
;     auto rr = __builtin_amdgcn_permlane32_swap(__float_as_uint(v), __float_as_uint(v), false, false); return __uint_as_float(rr[0]) + __uint_as_float(rr[1]);
; }
; __global__ void __launch_bounds__(512, 2) fwd_kernel(Args a) {
;     ...
; #pragma unroll
;                     for (int hd = 0; hd < 8; ++hd) { const int base = hd < 6 ? 1184 + hd * 64 : 1568 + (hd - 6) * 64; float v = bf2f(rh[hd]);
;                         const float rstd = rsqrtf(wave_sum(v * v) * (1.0f / 64.0f) + EPS); v = v * rstd * (hd < 6 ? gq : gk);
;                         const float p = SWZ_XOR(v, 16); const float ov = (lane & 16) ? (p * cs[1] + v * cs[0]) : (v * cs[0] - p * cs[1]);
;                         z[base + lane] = (bf16_t)f2bf(ov); }
.LBB0_315:
	s_or_b64 exec, exec, s[4:5]
	v_lshlrev_b32_e32 v46, 16, v38
	v_lshlrev_b32_e32 v37, 16, v37
	v_mul_f32_e32 v18, v46, v46
	v_mul_f32_e32 v19, v37, v37
	s_nop 1
	v_mov_b32_dpp v18, v18 quad_perm:[1,0,3,2] row_mask:0xf bank_mask:0xf
	s_nop 1
	v_mov_b32_dpp v19, v19 quad_perm:[1,0,3,2] row_mask:0xf bank_mask:0xf
	s_mov_b32 s0, 0x358637bd
	v_lshlrev_b32_e32 v47, 16, v36
	v_lshlrev_b32_e32 v35, 16, v35
	s_waitcnt lgkmcnt(0)
	v_fmac_f32_e32 v18, v46, v46
	s_waitcnt lgkmcnt(0)
	v_fmac_f32_e32 v19, v37, v37
	s_nop 1
	v_mov_b32_dpp v20, v18 quad_perm:[2,3,0,1] row_mask:0xf bank_mask:0xf
	s_nop 1
	v_mov_b32_dpp v21, v19 quad_perm:[2,3,0,1] row_mask:0xf bank_mask:0xf
	v_mul_f32_e32 v49, v35, v35
	s_nop 1
	v_mov_b32_dpp v49, v49 quad_perm:[1,0,3,2] row_mask:0xf bank_mask:0xf
	s_mov_b64 s[4:5], 0x19000940
	s_waitcnt lgkmcnt(0)
	v_add_f32_e32 v18, v18, v20
	s_waitcnt lgkmcnt(0)
	v_add_f32_e32 v19, v19, v21
	s_nop 1
	v_mov_b32_dpp v20, v18 row_half_mirror row_mask:0xf bank_mask:0xf
	s_nop 1
	v_mov_b32_dpp v21, v19 row_half_mirror row_mask:0xf bank_mask:0xf
	s_waitcnt lgkmcnt(0)
	v_fmac_f32_e32 v49, v35, v35
	v_lshl_add_u64 v[26:27], v[16:17], 0, s[4:5]
	s_mov_b64 s[4:5], 0x190009c0
	s_waitcnt lgkmcnt(0)
	v_add_f32_e32 v18, v18, v20
	s_waitcnt lgkmcnt(0)
	v_add_f32_e32 v19, v19, v21
	s_nop 1
	v_mov_b32_dpp v20, v18 row_mirror row_mask:0xf bank_mask:0xf
	s_nop 1
	v_mov_b32_dpp v21, v19 row_mirror row_mask:0xf bank_mask:0xf
	v_lshl_add_u64 v[38:39], v[16:17], 0, s[4:5]
	v_lshlrev_b32_e32 v33, 16, v33
	s_mov_b64 s[4:5], 0x19000a40
	s_waitcnt lgkmcnt(0)
	v_add_f32_e32 v18, v18, v20
	s_waitcnt lgkmcnt(0)
	v_add_f32_e32 v22, v19, v21
	ds_swizzle_b32 v19, v18 offset:swizzle(SWAP,16)
	ds_swizzle_b32 v23, v22 offset:swizzle(SWAP,16)
	v_mov_b64_e32 v[20:21], s[0:1]
	v_lshl_add_u64 v[42:43], v[16:17], 0, s[4:5]
	s_mov_b64 s[4:5], 0x19000ac0
	s_waitcnt lgkmcnt(0)
	v_add_f32_e32 v19, v18, v19
	s_waitcnt lgkmcnt(0)
	v_add_f32_e32 v18, v22, v23
	v_mov_b32_e32 v23, v19
	v_mov_b32_e32 v22, v18
	s_nop 0
	v_permlane32_swap_b32_e32 v19, v23
	v_permlane32_swap_b32_e32 v18, v22
	v_pk_add_f32 v[18:19], v[18:19], v[22:23]
	v_lshl_add_u64 v[44:45], v[16:17], 0, s[4:5]
	v_pk_fma_f32 v[40:41], v[18:19], s[18:19], v[20:21] op_sel_hi:[1,0,0]
	v_lshlrev_b32_e32 v32, 16, v32
	v_mul_f32_e32 v18, 0x4b800000, v41
	v_cmp_gt_f32_e32 vcc, s44, v41
	v_mul_f32_e32 v48, 0x4b800000, v40
	v_lshlrev_b32_e32 v31, 16, v31
	v_cndmask_b32_e32 v18, v41, v18, vcc
	v_rsq_f32_e32 v18, v18
	s_mov_b64 s[4:5], 0x19000b40
	v_lshl_add_u64 v[24:25], v[16:17], 0, s[4:5]
	s_mov_b64 s[4:5], 0x19000bc0
	v_mul_f32_e32 v19, 0x45800000, v18
	v_cndmask_b32_e32 v18, v18, v19, vcc
	v_mul_f32_e32 v18, v18, v46
	v_mul_f32_e32 v41, v0, v18
	ds_swizzle_b32 v46, v41 offset:swizzle(SWAP,16)
	v_cmp_gt_f32_e32 vcc, s44, v40
	v_lshl_add_u64 v[22:23], v[16:17], 0, s[4:5]
	s_mov_b64 s[4:5], 0x19000c40
	v_cndmask_b32_e32 v40, v40, v48, vcc
	s_waitcnt lgkmcnt(0)
	v_mul_f32_e32 v36, v15, v46
	v_mul_f32_e32 v46, v47, v47
	s_nop 1
	v_mov_b32_dpp v46, v46 quad_perm:[1,0,3,2] row_mask:0xf bank_mask:0xf
	s_nop 1
	v_mov_b32_dpp v48, v49 quad_perm:[2,3,0,1] row_mask:0xf bank_mask:0xf
	v_cndmask_b32_e64 v36, v36, -v36, s[10:11]
	v_fmac_f32_e32 v36, v14, v41
	v_bfe_u32 v41, v36, 16, 1
	s_waitcnt lgkmcnt(0)
	v_fmac_f32_e32 v46, v47, v47
	s_nop 1
	v_mov_b32_dpp v50, v46 quad_perm:[2,3,0,1] row_mask:0xf bank_mask:0xf
	v_rsq_f32_e32 v40, v40
	v_add3_u32 v51, v36, v41, s13
	s_waitcnt lgkmcnt(0)
	v_add_f32_e32 v41, v49, v48
	s_nop 1
	v_mov_b32_dpp v48, v41 row_half_mirror row_mask:0xf bank_mask:0xf
	s_waitcnt lgkmcnt(0)
	v_add_f32_e32 v46, v46, v50
	s_nop 1
	v_mov_b32_dpp v50, v46 row_half_mirror row_mask:0xf bank_mask:0xf
	v_mul_f32_e32 v36, 0x45800000, v40
	v_cndmask_b32_e32 v36, v40, v36, vcc
	v_mul_f32_e32 v36, v36, v37
	s_waitcnt lgkmcnt(0)
	v_add_f32_e32 v37, v41, v48
	s_waitcnt lgkmcnt(0)
	v_add_f32_e32 v46, v46, v50
	s_nop 1
	v_mov_b32_dpp v49, v46 row_mirror row_mask:0xf bank_mask:0xf
	s_nop 1
	v_mov_b32_dpp v40, v37 row_mirror row_mask:0xf bank_mask:0xf
	v_mul_f32_e32 v48, v0, v36
	global_store_short_d16_hi v[26:27], v51, off
	v_lshl_add_u64 v[18:19], v[16:17], 0, s[4:5]
	s_waitcnt lgkmcnt(0)
	v_add_f32_e32 v41, v46, v49
	s_waitcnt lgkmcnt(0)
	v_add_f32_e32 v36, v37, v40
	ds_swizzle_b32 v46, v41 offset:swizzle(SWAP,16)
	ds_swizzle_b32 v40, v36 offset:swizzle(SWAP,16)
	ds_swizzle_b32 v49, v48 offset:swizzle(SWAP,16)
	s_mov_b64 s[4:5], 0x19000cc0
	s_add_i32 s22, s22, s54
	s_waitcnt lgkmcnt(0)
	v_add_f32_e32 v37, v41, v46
	s_waitcnt lgkmcnt(0)
	v_add_f32_e32 v36, v36, v40
	v_mov_b32_e32 v41, v37
	v_mov_b32_e32 v40, v36
	s_nop 0
	v_permlane32_swap_b32_e32 v37, v41
	v_permlane32_swap_b32_e32 v36, v40
	v_pk_add_f32 v[36:37], v[36:37], v[40:41]
	s_waitcnt lgkmcnt(0)
	v_mul_f32_e32 v26, v15, v49
	v_pk_fma_f32 v[36:37], v[36:37], s[18:19], v[20:21] op_sel_hi:[1,0,0]
	v_cndmask_b32_e64 v26, v26, -v26, s[10:11]
	v_mul_f32_e32 v40, 0x4b800000, v37
	v_cmp_gt_f32_e32 vcc, s44, v37
	v_fmac_f32_e32 v26, v14, v48
	v_lshl_add_u64 v[16:17], v[16:17], 0, s[4:5]
	v_cndmask_b32_e32 v37, v37, v40, vcc
	v_rsq_f32_e32 v37, v37
	v_bfe_u32 v40, v26, 16, 1
	v_add3_u32 v26, v26, v40, s13
	global_store_short_d16_hi v[38:39], v26, off
	v_mul_f32_e32 v27, 0x45800000, v37
	v_cndmask_b32_e32 v27, v37, v27, vcc
	v_mul_f32_e32 v27, v27, v47
	v_mul_f32_e32 v27, v0, v27
	ds_swizzle_b32 v37, v27 offset:swizzle(SWAP,16)
	v_mul_f32_e32 v39, v33, v33
	s_nop 1
	v_mov_b32_dpp v39, v39 quad_perm:[1,0,3,2] row_mask:0xf bank_mask:0xf
	v_mul_f32_e32 v38, 0x4b800000, v36
	v_cmp_gt_f32_e32 vcc, s44, v36
	s_waitcnt lgkmcnt(0)
; __device__ __forceinline__ float bf2f(bf16_t v) { return __uint_as_float((unsigned)v << 16); }
; __device__ __forceinline__ unsigned f2bf(float f) { unsigned u = __float_as_uint(f); return (u + 0x7fffu + ((u >> 16) & 1u)) >> 16; }
; #define SWZ_XOR(v, X) __int_as_float(__builtin_amdgcn_ds_swizzle(__float_as_int(v), ((X) << 10) | 0x1f))
; __device__ __forceinline__ float wave_sum(float v) {
;     v += SWZ_XOR(v, 1); v += SWZ_XOR(v, 2); v += SWZ_XOR(v, 4); v += SWZ_XOR(v, 8); v += SWZ_XOR(v, 16);
;     auto rr = __builtin_amdgcn_permlane32_swap(__float_as_uint(v), __float_as_uint(v), false, false); return __uint_as_float(rr[0]) + __uint_as_float(rr[1]);
; }
; __global__ void __launch_bounds__(512, 2) fwd_kernel(Args a) {
;     ...
; #pragma unroll
;                     for (int hd = 0; hd < 8; ++hd) { const int base = hd < 6 ? 1184 + hd * 64 : 1568 + (hd - 6) * 64; float v = bf2f(rh[hd]);
;                         const float rstd = rsqrtf(wave_sum(v * v) * (1.0f / 64.0f) + EPS); v = v * rstd * (hd < 6 ? gq : gk);
;                         const float p = SWZ_XOR(v, 16); const float ov = (lane & 16) ? (p * cs[1] + v * cs[0]) : (v * cs[0] - p * cs[1]);
;                         z[base + lane] = (bf16_t)f2bf(ov); }
	v_mul_f32_e32 v26, v15, v37
	v_lshlrev_b32_e32 v37, 16, v34
	v_mul_f32_e32 v34, v37, v37
	s_nop 1
	v_mov_b32_dpp v34, v34 quad_perm:[1,0,3,2] row_mask:0xf bank_mask:0xf
	s_waitcnt lgkmcnt(0)
	v_fmac_f32_e32 v39, v33, v33
	v_cndmask_b32_e32 v36, v36, v38, vcc
	s_nop 1
	v_mov_b32_dpp v38, v39 quad_perm:[2,3,0,1] row_mask:0xf bank_mask:0xf
	v_cndmask_b32_e64 v26, v26, -v26, s[10:11]
	s_waitcnt lgkmcnt(0)
	v_fmac_f32_e32 v34, v37, v37
	s_nop 1
	v_mov_b32_dpp v40, v34 quad_perm:[2,3,0,1] row_mask:0xf bank_mask:0xf
	v_fmac_f32_e32 v26, v14, v27
	v_bfe_u32 v27, v26, 16, 1
	v_add3_u32 v41, v26, v27, s13
	s_waitcnt lgkmcnt(0)
	v_add_f32_e32 v27, v39, v38
	s_waitcnt lgkmcnt(0)
	v_add_f32_e32 v34, v34, v40
	v_rsq_f32_e32 v36, v36
	s_nop 1
	v_mov_b32_dpp v40, v34 row_half_mirror row_mask:0xf bank_mask:0xf
	s_nop 1
	v_mov_b32_dpp v38, v27 row_half_mirror row_mask:0xf bank_mask:0xf
	v_lshl_add_u64 v[6:7], v[6:7], 0, s[76:77]
	v_mul_f32_e32 v26, 0x45800000, v36
	v_cndmask_b32_e32 v26, v36, v26, vcc
	s_waitcnt lgkmcnt(0)
	v_add_f32_e32 v34, v34, v40
	s_waitcnt lgkmcnt(0)
	v_add_f32_e32 v27, v27, v38
	s_nop 1
	v_mov_b32_dpp v39, v34 row_mirror row_mask:0xf bank_mask:0xf
	v_mul_f32_e32 v26, v26, v35
	s_nop 1
	v_mov_b32_dpp v35, v27 row_mirror row_mask:0xf bank_mask:0xf
	v_mul_f32_e32 v38, v0, v26
	v_lshl_add_u64 v[8:9], v[8:9], 0, s[70:71]
	s_waitcnt lgkmcnt(0)
	v_add_f32_e32 v34, v34, v39
	ds_swizzle_b32 v36, v34 offset:swizzle(SWAP,16)
	s_waitcnt lgkmcnt(0)
	v_add_f32_e32 v26, v27, v35
	ds_swizzle_b32 v40, v26 offset:swizzle(SWAP,16)
	ds_swizzle_b32 v39, v38 offset:swizzle(SWAP,16)
	v_lshl_add_u64 v[10:11], v[10:11], 0, s[70:71]
	s_waitcnt lgkmcnt(0)
	v_add_f32_e32 v27, v34, v36
	v_mov_b32_e32 v35, v27
	s_waitcnt lgkmcnt(0)
	v_add_f32_e32 v26, v26, v40
	v_mov_b32_e32 v34, v26
	v_permlane32_swap_b32_e32 v27, v35
	s_nop 0
	v_permlane32_swap_b32_e32 v26, v34
	v_pk_add_f32 v[26:27], v[26:27], v[34:35]
	v_lshl_add_u64 v[2:3], v[2:3], 0, s[70:71]
	v_pk_fma_f32 v[26:27], v[26:27], s[18:19], v[20:21] op_sel_hi:[1,0,0]
	v_lshl_add_u64 v[12:13], v[12:13], 0, s[70:71]
	v_mul_f32_e32 v34, 0x4b800000, v27
	v_cmp_gt_f32_e32 vcc, s44, v27
	s_cmp_gt_i32 s22, 0x13fff
	v_lshl_add_u64 v[4:5], v[4:5], 0, s[70:71]
	v_cndmask_b32_e32 v27, v27, v34, vcc
	v_rsq_f32_e32 v27, v27
	s_waitcnt lgkmcnt(0)
	v_mul_f32_e32 v34, v15, v39
	v_cndmask_b32_e64 v34, v34, -v34, s[10:11]
	v_fmac_f32_e32 v34, v14, v38
	v_mul_f32_e32 v35, 0x45800000, v27
	v_cndmask_b32_e32 v27, v27, v35, vcc
	v_mul_f32_e32 v27, v27, v37
	v_mul_f32_e32 v27, v0, v27
	ds_swizzle_b32 v35, v27 offset:swizzle(SWAP,16)
	v_bfe_u32 v36, v34, 16, 1
	v_add3_u32 v34, v34, v36, s13
	global_store_short_d16_hi v[44:45], v34, off
	v_cmp_gt_f32_e32 vcc, s44, v26
	s_waitcnt lgkmcnt(0)
	v_mul_f32_e32 v34, v15, v35
	v_cndmask_b32_e64 v34, v34, -v34, s[10:11]
	v_fmac_f32_e32 v34, v14, v27
	v_bfe_u32 v27, v34, 16, 1
	v_add3_u32 v27, v34, v27, s13
	v_mul_f32_e32 v34, 0x4b800000, v26
	v_cndmask_b32_e32 v26, v26, v34, vcc
	v_mul_f32_e32 v34, v32, v32
	s_nop 1
	v_mov_b32_dpp v34, v34 quad_perm:[1,0,3,2] row_mask:0xf bank_mask:0xf
	v_mul_f32_e32 v35, v31, v31
	s_nop 1
	v_mov_b32_dpp v35, v35 quad_perm:[1,0,3,2] row_mask:0xf bank_mask:0xf
	global_store_short_d16_hi v[24:25], v27, off
	v_rsq_f32_e32 v26, v26
	s_waitcnt lgkmcnt(0)
	v_fmac_f32_e32 v34, v32, v32
	s_nop 1
	v_mov_b32_dpp v36, v34 quad_perm:[2,3,0,1] row_mask:0xf bank_mask:0xf
	s_waitcnt lgkmcnt(0)
	v_fmac_f32_e32 v35, v31, v31
	s_nop 1
	v_mov_b32_dpp v25, v35 quad_perm:[2,3,0,1] row_mask:0xf bank_mask:0xf
	v_mul_f32_e32 v24, 0x45800000, v26
	v_cndmask_b32_e32 v24, v26, v24, vcc
	s_waitcnt lgkmcnt(0)
	v_add_f32_e32 v27, v34, v36
	s_nop 1
	v_mov_b32_dpp v34, v27 row_half_mirror row_mask:0xf bank_mask:0xf
	s_waitcnt lgkmcnt(0)
	v_add_f32_e32 v25, v35, v25
	s_nop 1
	v_mov_b32_dpp v26, v25 row_half_mirror row_mask:0xf bank_mask:0xf
	v_mul_f32_e32 v24, v24, v33
	global_store_short_d16_hi v[42:43], v41, off
	s_waitcnt lgkmcnt(0)
	v_add_f32_e32 v27, v27, v34
	v_mul_f32_e32 v34, v0, v24
	ds_swizzle_b32 v24, v34 offset:swizzle(SWAP,16)
	s_waitcnt lgkmcnt(0)
	v_add_f32_e32 v25, v25, v26
	s_nop 1
	v_mov_b32_dpp v33, v27 row_mirror row_mask:0xf bank_mask:0xf
	s_nop 1
	v_mov_b32_dpp v26, v25 row_mirror row_mask:0xf bank_mask:0xf
	s_waitcnt lgkmcnt(0)
	v_mul_f32_e32 v24, v15, v24
	v_cndmask_b32_e64 v35, v24, -v24, s[10:11]
	s_waitcnt lgkmcnt(0)
	v_add_f32_e32 v27, v27, v33
	s_waitcnt lgkmcnt(0)
	v_add_f32_e32 v24, v25, v26
	ds_swizzle_b32 v33, v27 offset:swizzle(SWAP,16)
	ds_swizzle_b32 v26, v24 offset:swizzle(SWAP,16)
	v_fmac_f32_e32 v35, v14, v34
	s_waitcnt lgkmcnt(0)
	v_add_f32_e32 v25, v27, v33
	s_waitcnt lgkmcnt(0)
	v_add_f32_e32 v24, v24, v26
	v_mov_b32_e32 v27, v25
	v_mov_b32_e32 v26, v24
	s_nop 0
	v_permlane32_swap_b32_e32 v25, v27
	v_permlane32_swap_b32_e32 v24, v26
	v_pk_add_f32 v[24:25], v[24:25], v[26:27]
	s_nop 0
	v_pk_fma_f32 v[20:21], v[24:25], s[18:19], v[20:21] op_sel_hi:[1,0,0]
	s_nop 0
	v_mul_f32_e32 v24, 0x4b800000, v21
	v_cmp_gt_f32_e32 vcc, s44, v21
	v_mul_f32_e32 v26, 0x4b800000, v20
	s_nop 0
	v_cndmask_b32_e32 v21, v21, v24, vcc
	v_rsq_f32_e32 v21, v21
	v_bfe_u32 v24, v35, 16, 1
	v_add3_u32 v24, v35, v24, s13
	global_store_short_d16_hi v[22:23], v24, off
	v_mul_f32_e32 v25, 0x45800000, v21
	v_cndmask_b32_e32 v21, v21, v25, vcc
	v_cmp_gt_f32_e32 vcc, s44, v20
	v_mul_f32_e32 v21, v21, v32
	v_mul_f32_e32 v21, v28, v21
	v_cndmask_b32_e32 v20, v20, v26, vcc
	v_rsq_f32_e32 v20, v20
	ds_swizzle_b32 v25, v21 offset:swizzle(SWAP,16)
	v_mul_f32_e32 v23, 0x45800000, v20
	v_cndmask_b32_e32 v20, v20, v23, vcc
	v_mul_f32_e32 v20, v20, v31
	v_mul_f32_e32 v20, v28, v20
	ds_swizzle_b32 v23, v20 offset:swizzle(SWAP,16)
	s_waitcnt lgkmcnt(0)
	v_mul_f32_e32 v22, v15, v25
	v_cndmask_b32_e64 v22, v22, -v22, s[10:11]
	v_fmac_f32_e32 v22, v14, v21
	v_bfe_u32 v21, v22, 16, 1
	s_waitcnt lgkmcnt(0)
	v_mul_f32_e32 v15, v15, v23
	v_cndmask_b32_e64 v15, v15, -v15, s[10:11]
	v_fmac_f32_e32 v15, v14, v20
	v_bfe_u32 v14, v15, 16, 1
	v_add3_u32 v21, v22, v21, s13
	v_add3_u32 v14, v15, v14, s13
	global_store_short_d16_hi v[18:19], v21, off
	global_store_short_d16_hi v[16:17], v14, off
	s_cbranch_scc1 .LBB0_319
; __global__ void __launch_bounds__(512, 2) fwd_kernel(Args a) {
;     ...
;                 for (int m = gw; m < MTOK; m += NGW) {
;                     bf16_t* z = Z + (size_t)m * ZC; const int pos = m & (SEQ - 1), rowp = pos >> 6, colp = pos & 63;
;                     const int grp = lane >> 2, ia = lane & 3, basea = (grp < 8 ? 0 : 256) + (grp & 7) * 32;
;                     const bf16_t ra1 = z[basea + ia], ra2 = z[basea + 4 + ia];
;                     const u32x2 wq = *(const u32x2*)(z + 768 + 4 * lane);
;                     const unsigned wkv = *(const unsigned*)(z + 1024 + 2 * lane);
;                     const bf16_t rk1 = z[1152 + (lane & 15)], rk2 = z[1168 + (lane & 15)];
;                     bf16_t rh[8];
; #pragma unroll
;                     for (int hd = 0; hd < 8; ++hd) rh[hd] = z[(hd < 6 ? 1184 + hd * 64 : 1568 + (hd - 6) * 64) + lane];
;                     const f32x2_t csa = *(const f32x2_t*)(taba + (size_t)(pos * 4 + ia) * 2);
;                     const f32x2_t csk = *(const f32x2_t*)(tab32 + (size_t)(pos * 16 + (lane & 15)) * 2);
;                     const int pp = lane < 32 ? rowp : colp; const f32x2_t cs = *(const f32x2_t*)(tab32 + (size_t)(pp * 16 + (lane & 15)) * 2);
;                     asm volatile("" ::: "memory");
;                     { const float x1 = bf2f(ra1), x2 = bf2f(ra2);
;                       z[basea + ia] = (bf16_t)f2bf(x1 * csa[0] - x2 * csa[1]); z[basea + 4 + ia] = (bf16_t)f2bf(x1 * csa[1] + x2 * csa[0]); }
;                     { const float v0 = __uint_as_float(wq.x << 16), v1 = __uint_as_float(wq.x & 0xffff0000u), v2 = __uint_as_float(wq.y << 16), v3 = __uint_as_float(wq.y & 0xffff0000u);
;                       const float rstd = rsqrtf(wave_sum((v0 * v0 + v1 * v1) + (v2 * v2 + v3 * v3)) * (1.0f / 256.0f) + EPS);
;                       u32x2 o; o.x = pk2(v0 * rstd, v1 * rstd); o.y = pk2(v2 * rstd, v3 * rstd); *(u32x2*)(z + 768 + 4 * lane) = o; }
;                     { const float v0 = __uint_as_float(wkv << 16), v1 = __uint_as_float(wkv & 0xffff0000u);
;                       const float rstd = rsqrtf(wave_sum(v0 * v0 + v1 * v1) * (1.0f / 128.0f) + EPS);
;                       *(unsigned*)(z + 1024 + 2 * lane) = pk2(v0 * rstd, v1 * rstd); }
;                     if (lane < 16) { const float x1 = bf2f(rk1), x2 = bf2f(rk2);
.LBB0_316:
	v_readlane_b32 s36, v252, 21
	v_readlane_b32 s38, v252, 23
	v_readlane_b32 s39, v252, 24
	s_and_b32 s0, s22, 0x1fff
	v_readlane_b32 s14, v252, 19
	v_lshl_add_u64 v[14:15], s[38:39], 0, v[4:5]
	v_add_co_u32_e32 v14, vcc, 0x19000000, v14
	v_lshl_add_u64 v[22:23], s[38:39], 0, v[10:11]
	v_lshl_add_u64 v[18:19], s[38:39], 0, v[8:9]
	v_addc_co_u32_e32 v15, vcc, 0, v15, vcc
	v_lshl_add_u64 v[16:17], s[38:39], 0, v[2:3]
	global_load_dwordx2 v[24:25], v[22:23], off
	global_load_dword v41, v[18:19], off
	global_load_ushort v39, v[14:15], off offset:2304
	global_load_ushort v40, v[14:15], off offset:2336
	v_add_co_u32_e32 v14, vcc, 0x19000000, v16
	v_readlane_b32 s15, v252, 20
	s_nop 0
	v_addc_co_u32_e32 v15, vcc, 0, v17, vcc
	global_load_ushort v38, v[14:15], off offset:2368
	global_load_ushort v37, v[14:15], off offset:2496
	global_load_ushort v36, v[14:15], off offset:2624
	global_load_ushort v35, v[14:15], off offset:2752
	global_load_ushort v34, v[14:15], off offset:2880
	global_load_ushort v33, v[14:15], off offset:3008
	global_load_ushort v32, v[14:15], off offset:3136
	global_load_ushort v31, v[14:15], off offset:3264
	v_lshl_or_b32 v14, s0, 5, v30
	global_load_dwordx2 v[26:27], v14, s[14:15]
	v_lshlrev_b32_e32 v14, 2, v29
	s_bfe_u32 s4, s22, 0x70006
	s_and_b32 s5, s22, 63
	v_lshl_or_b32 v15, s0, 7, v14
	v_lshl_add_u64 v[42:43], s[38:39], 0, v[12:13]
	global_load_dwordx2 v[20:21], v15, s[66:67]
	v_mov_b32_e32 v15, s5
	v_mov_b32_e32 v44, s4
	s_mov_b32 s0, 0x19000000
	v_cndmask_b32_e64 v15, v15, v44, s[6:7]
	v_add_co_u32_e32 v42, vcc, s0, v42
	v_lshl_or_b32 v14, v15, 7, v14
	s_nop 0
	v_addc_co_u32_e32 v43, vcc, 0, v43, vcc
	global_load_dwordx2 v[14:15], v14, s[66:67]
	s_nop 0
	global_load_ushort v44, v[42:43], off
	global_load_ushort v45, v[42:43], off offset:8
	v_readlane_b32 s37, v252, 22
	s_waitcnt vmcnt(1)
	v_lshlrev_b32_e32 v44, 16, v44
	s_waitcnt vmcnt(0)
	v_lshlrev_b32_e32 v45, 16, v45
	v_mul_f32_e32 v46, v27, v45
	v_fma_f32 v46, v26, v44, -v46
	v_mul_f32_e32 v26, v26, v45
	v_fmac_f32_e32 v26, v27, v44
	v_bfe_u32 v47, v46, 16, 1
	v_bfe_u32 v27, v26, 16, 1
	v_add3_u32 v46, v46, v47, s13
	v_add3_u32 v26, v26, v27, s13
	global_store_short_d16_hi v[42:43], v46, off
	global_store_short_d16_hi v[42:43], v26, off offset:8
	v_and_b32_e32 v27, 0xffff0000, v25
	v_and_b32_e32 v43, 0xffff0000, v24
	v_lshlrev_b32_e32 v26, 16, v25
	v_lshlrev_b32_e32 v42, 16, v24
	v_mov_b32_e32 v44, v43
	v_mov_b32_e32 v45, v27
	v_mov_b32_e32 v24, v42
	v_mov_b32_e32 v25, v26
	v_pk_mul_f32 v[44:45], v[44:45], v[44:45]
	v_lshlrev_b32_e32 v46, 16, v41
	v_pk_fma_f32 v[24:25], v[24:25], v[24:25], v[44:45]
	v_and_b32_e32 v47, 0xffff0000, v41
	v_add_f32_e32 v24, v24, v25
	s_nop 1
	v_mov_b32_dpp v25, v24 quad_perm:[1,0,3,2] row_mask:0xf bank_mask:0xf
	v_pk_mul_f32 v[48:49], v[46:47], v[46:47]
	s_waitcnt lgkmcnt(0)
	v_add_f32_e32 v24, v24, v25
	s_nop 1
	v_mov_b32_dpp v25, v24 quad_perm:[2,3,0,1] row_mask:0xf bank_mask:0xf
	s_waitcnt lgkmcnt(0)
	v_add_f32_e32 v24, v24, v25
	s_nop 1
	v_mov_b32_dpp v25, v24 row_half_mirror row_mask:0xf bank_mask:0xf
	s_waitcnt lgkmcnt(0)
	v_add_f32_e32 v24, v24, v25
	s_nop 1
	v_mov_b32_dpp v25, v24 row_mirror row_mask:0xf bank_mask:0xf
	s_waitcnt lgkmcnt(0)
	v_add_f32_e32 v24, v24, v25
	ds_swizzle_b32 v25, v24 offset:swizzle(SWAP,16)
	s_waitcnt lgkmcnt(0)
	v_add_f32_e32 v25, v24, v25
	v_add_f32_e32 v24, v48, v49
	s_nop 1
	v_mov_b32_dpp v41, v24 quad_perm:[1,0,3,2] row_mask:0xf bank_mask:0xf
	v_mov_b32_e32 v45, v25
	s_nop 1
	v_permlane32_swap_b32_e32 v25, v45
	s_waitcnt lgkmcnt(0)
	v_add_f32_e32 v24, v24, v41
	s_nop 1
	v_mov_b32_dpp v41, v24 quad_perm:[2,3,0,1] row_mask:0xf bank_mask:0xf
	s_waitcnt lgkmcnt(0)
	v_add_f32_e32 v24, v24, v41
	s_nop 1
	v_mov_b32_dpp v41, v24 row_half_mirror row_mask:0xf bank_mask:0xf
	s_waitcnt lgkmcnt(0)
	v_add_f32_e32 v24, v24, v41
	s_nop 1
	v_mov_b32_dpp v41, v24 row_mirror row_mask:0xf bank_mask:0xf
	s_waitcnt lgkmcnt(0)
	v_add_f32_e32 v24, v24, v41
	ds_swizzle_b32 v41, v24 offset:swizzle(SWAP,16)
	s_waitcnt lgkmcnt(0)
	v_add_f32_e32 v24, v24, v41
	v_mov_b32_e32 v44, v24
	s_nop 1
	v_permlane32_swap_b32_e32 v24, v44
	v_pk_add_f32 v[24:25], v[24:25], v[44:45]
	s_nop 0
	v_pk_fma_f32 v[24:25], v[24:25], s[16:17], v[200:201] op_sel_hi:[1,1,0]
	s_nop 0
	v_mul_f32_e32 v41, 0x4b800000, v25
	v_cmp_gt_f32_e64 s[14:15], s44, v25
	v_cmp_gt_f32_e32 vcc, s44, v24
	s_nop 0
	v_cndmask_b32_e64 v25, v25, v41, s[14:15]
	v_rsq_f32_e32 v25, v25
	s_nop 0
	v_mul_f32_e32 v41, 0x45800000, v25
	v_cndmask_b32_e64 v44, v25, v41, s[14:15]
	v_pk_mul_f32 v[42:43], v[44:45], v[42:43] op_sel_hi:[0,1]
	v_pk_mul_f32 v[26:27], v[44:45], v[26:27] op_sel_hi:[0,1]
	v_cvt_pk_bf16_f32 v42, v42, v43
	v_cvt_pk_bf16_f32 v43, v26, v27
	global_store_dwordx2 v[22:23], v[42:43], off
	v_mul_f32_e32 v22, 0x4b800000, v24
	v_cndmask_b32_e32 v22, v24, v22, vcc
	v_rsq_f32_e32 v22, v22
	s_nop 0
	v_mul_f32_e32 v23, 0x45800000, v22
	v_cndmask_b32_e32 v22, v22, v23, vcc
	v_pk_mul_f32 v[22:23], v[22:23], v[46:47] op_sel_hi:[0,1]
	v_cvt_pk_bf16_f32 v22, v22, v23
	global_store_dword v[18:19], v22, off
	s_and_saveexec_b64 s[4:5], s[8:9]
	s_cbranch_execz .LBB0_315
	v_lshlrev_b32_e32 v22, 16, v40
	v_lshlrev_b32_e32 v18, 16, v39
	v_pk_mul_f32 v[22:23], v[20:21], v[22:23] op_sel:[1,0] op_sel_hi:[0,0]
	v_readlane_b32 s36, v252, 21
	v_pk_fma_f32 v[24:25], v[20:21], v[18:19], v[22:23] neg_lo:[0,0,1] neg_hi:[0,0,1]
	v_pk_fma_f32 v[18:19], v[20:21], v[18:19], v[22:23] op_sel_hi:[1,0,1]
	v_readlane_b32 s38, v252, 23
	v_readlane_b32 s39, v252, 24
	v_cvt_pk_bf16_f32 v20, v24, v19
	v_readlane_b32 s37, v252, 22
	v_lshl_add_u64 v[18:19], s[38:39], 0, v[6:7]
	global_store_dword v[18:19], v20, off
	s_branch .LBB0_315
